# v9 + FoX step-B: deferred row-sum chain moved into the QK block's idle VALU slots; PV block V fragment reads issued 4 MFMAs ahead into freed registers
# baseline (speedup 1.0000x reference)
.LBB0_349:
	ds_read_b128 v[60:63], v192 offset:96
	ds_read_b128 v[56:59], v192 offset:64
	ds_read_b128 v[48:51], v192
	ds_read_b128 v[52:55], v192 offset:32
	v_add_u32_e32 v196, s64, v144
	ds_read_b128 v[238:241], v196
	ds_read_b128 v[242:245], v189 offset:60416
	ds_read_b128 v[32:35], v192 offset:128
	ds_read_b128 v[36:39], v192 offset:160
	ds_read_b128 v[40:43], v192 offset:192
	ds_read_b128 v[44:47], v192 offset:224
	ds_read_b128 v[246:249], v196 offset:512
	ds_read_b128 v[250:253], v189 offset:61440
	s_waitcnt lgkmcnt(6)
	v_mfma_f32_32x32x16_bf16 v[48:63], v[238:241], v[242:245], v[48:63]
	ds_read_b128 v[238:241], v196 offset:2080
	v_max3_f32 v237, v80, s94, v81
	v_max3_f32 v237, v237, v82, v83
	v_add_f32_e32 v198, 0, v198
	v_add_f32_e32 v198, v199, v198
	v_add_f32_e32 v198, v200, v198
	v_add_f32_e32 v198, v201, v198
	v_add_f32_e32 v198, v202, v198
	s_waitcnt lgkmcnt(2)
	v_mfma_f32_32x32x16_bf16 v[32:47], v[246:249], v[242:245], v[32:47]
	ds_read_b128 v[242:245], v196 offset:2592
	ds_read_b128 v[246:249], v189 offset:62464
	v_max3_f32 v237, v237, v84, v85
	v_max3_f32 v237, v237, v86, v87
	v_add_f32_e32 v198, v203, v198
	v_add_f32_e32 v198, v204, v198
	v_add_f32_e32 v198, v205, v198
	v_add_f32_e32 v198, v206, v198
	v_add_f32_e32 v198, v207, v198
	s_waitcnt lgkmcnt(2)
	v_mfma_f32_32x32x16_bf16 v[48:63], v[238:241], v[250:253], v[48:63]
	ds_read_b128 v[238:241], v196 offset:4160
	v_max3_f32 v237, v237, v88, v89
	v_max3_f32 v237, v237, v90, v91
	v_add_f32_e32 v198, v208, v198
	v_add_f32_e32 v198, v209, v198
	v_add_f32_e32 v198, v210, v198
	v_add_f32_e32 v198, v211, v198
	v_add_f32_e32 v198, v212, v198
	s_waitcnt lgkmcnt(2)
	v_mfma_f32_32x32x16_bf16 v[32:47], v[242:245], v[250:253], v[32:47]
	ds_read_b128 v[242:245], v196 offset:4672
	ds_read_b128 v[250:253], v189 offset:63488
	v_max3_f32 v237, v237, v92, v93
	v_max3_f32 v237, v237, v94, v95
	v_add_f32_e32 v198, v213, v198
	v_add_f32_e32 v198, v214, v198
	v_add_f32_e32 v198, v215, v198
	v_add_f32_e32 v198, v216, v198
	v_add_f32_e32 v198, v217, v198
	s_waitcnt lgkmcnt(2)
	v_mfma_f32_32x32x16_bf16 v[48:63], v[238:241], v[246:249], v[48:63]
	ds_read_b128 v[238:241], v196 offset:6240
	v_max3_f32 v237, v237, v64, v65
	v_max3_f32 v237, v237, v66, v67
	v_add_f32_e32 v198, v218, v198
	v_add_f32_e32 v198, v219, v198
	v_add_f32_e32 v198, v220, v198
	v_add_f32_e32 v198, v221, v198
	v_add_f32_e32 v198, v222, v198
	s_waitcnt lgkmcnt(2)
	v_mfma_f32_32x32x16_bf16 v[32:47], v[242:245], v[246:249], v[32:47]
	ds_read_b128 v[242:245], v196 offset:6752
	v_max3_f32 v237, v237, v68, v69
	v_max3_f32 v237, v237, v70, v71
	v_add_f32_e32 v198, v223, v198
	v_add_f32_e32 v198, v224, v198
	v_add_f32_e32 v198, v225, v198
	v_add_f32_e32 v198, v226, v198
	v_add_f32_e32 v198, v227, v198
	s_waitcnt lgkmcnt(1)
	v_mfma_f32_32x32x16_bf16 v[48:63], v[238:241], v[250:253], v[48:63]
	v_max3_f32 v196, v237, v72, v73
	v_max3_f32 v196, v196, v74, v75
	v_add_f32_e32 v198, v228, v198
	v_add_f32_e32 v198, v229, v198
	v_fmac_f32_e32 v198, v191, v197
	s_waitcnt lgkmcnt(0)
	v_mfma_f32_32x32x16_bf16 v[32:47], v[242:245], v[250:253], v[32:47]
	v_max3_f32 v196, v196, v76, v77
	v_max3_f32 v196, v196, v78, v79
	v_mov_b32_e32 v237, v196
	v_mov_b32_e32 v238, v196
	s_nop 1
	v_permlane32_swap_b32_e32 v237, v238
	v_cndmask_b32_e64 v237, v237, v238, s[36:37]
	v_max_f32_e32 v237, v237, v237
	v_max_f32_e32 v196, v196, v237
	v_add_f32_e32 v237, 0x40c00000, v236
	v_cmp_gt_f32_e32 vcc, v196, v237
	s_nop 1
	v_cndmask_b32_e32 v196, v236, v196, vcc
	v_sub_f32_e32 v237, v236, v196
	v_exp_f32_e32 v237, v237
	v_cmp_neq_f32_e32 vcc, v196, v236
	s_cbranch_vccz .LBB0_353
	s_and_saveexec_b64 vcc, s[36:37]
	ds_write_b32 v176, v237 offset:58112
	s_or_b64 exec, exec, vcc
	v_add_u32_e32 v236, s75, v108
	ds_read_b128 v[238:241], v236 offset:58208
	ds_read_b128 v[242:245], v236 offset:58176
	ds_read_b128 v[246:249], v236 offset:58144
	ds_read_b128 v[250:253], v236 offset:58112
	s_waitcnt lgkmcnt(3)
	v_pk_mul_f32 v[12:13], v[12:13], v[238:239]
	s_waitcnt lgkmcnt(2)
	v_pk_mul_f32 v[8:9], v[8:9], v[242:243]
	s_waitcnt lgkmcnt(1)
	v_pk_mul_f32 v[4:5], v[4:5], v[246:247]
	v_pk_mul_f32 v[14:15], v[14:15], v[240:241]
	v_pk_mul_f32 v[10:11], v[10:11], v[244:245]
	v_pk_mul_f32 v[6:7], v[6:7], v[248:249]
	s_waitcnt lgkmcnt(0)
	v_pk_mul_f32 v[2:3], v[2:3], v[252:253]
	v_pk_mul_f32 v[0:1], v[0:1], v[250:251]
	v_pk_mul_f32 v[28:29], v[28:29], v[238:239]
	v_pk_mul_f32 v[24:25], v[24:25], v[242:243]
	v_pk_mul_f32 v[20:21], v[20:21], v[246:247]
	v_pk_mul_f32 v[30:31], v[30:31], v[240:241]
	v_pk_mul_f32 v[26:27], v[26:27], v[244:245]
	v_pk_mul_f32 v[22:23], v[22:23], v[248:249]
	v_pk_mul_f32 v[18:19], v[18:19], v[252:253]
	v_pk_mul_f32 v[16:17], v[16:17], v[250:251]
.LBB0_353:
	ds_read_b64_tr_b16 v[200:201], v195 offset:16640
	ds_read_b64_tr_b16 v[202:203], v195 offset:17152
	ds_read_b64_tr_b16 v[204:205], v195 offset:20800
	ds_read_b64_tr_b16 v[206:207], v195 offset:21312
	ds_read_b64_tr_b16 v[208:209], v195 offset:17664
	ds_read_b64_tr_b16 v[210:211], v195 offset:18176
	ds_read_b64_tr_b16 v[212:213], v195 offset:21824
	ds_read_b64_tr_b16 v[214:215], v195 offset:22336
	v_sub_f32_e32 v80, v80, v196
	v_sub_f32_e32 v81, v81, v196
	v_sub_f32_e32 v82, v82, v196
	v_sub_f32_e32 v83, v83, v196
	v_sub_f32_e32 v84, v84, v196
	v_sub_f32_e32 v85, v85, v196
	v_sub_f32_e32 v86, v86, v196
	v_sub_f32_e32 v87, v87, v196
	v_exp_f32_e32 v80, v80
	v_exp_f32_e32 v81, v81
	v_exp_f32_e32 v82, v82
	v_exp_f32_e32 v83, v83
	v_exp_f32_e32 v84, v84
	v_exp_f32_e32 v85, v85
	v_exp_f32_e32 v86, v86
	v_exp_f32_e32 v87, v87
	v_cvt_pk_bf16_f32 v238, v80, v81
	v_cvt_pk_bf16_f32 v239, v82, v83
	v_cvt_pk_bf16_f32 v240, v84, v85
	v_cvt_pk_bf16_f32 v241, v86, v87
	v_sub_f32_e32 v88, v88, v196
	v_sub_f32_e32 v89, v89, v196
	v_sub_f32_e32 v90, v90, v196
	v_sub_f32_e32 v91, v91, v196
	v_sub_f32_e32 v92, v92, v196
	v_sub_f32_e32 v93, v93, v196
	v_sub_f32_e32 v94, v94, v196
	v_sub_f32_e32 v95, v95, v196
	v_exp_f32_e32 v88, v88
	v_exp_f32_e32 v89, v89
	v_exp_f32_e32 v90, v90
	v_exp_f32_e32 v91, v91
	v_exp_f32_e32 v92, v92
	v_exp_f32_e32 v93, v93
	v_exp_f32_e32 v94, v94
	v_exp_f32_e32 v95, v95
	s_waitcnt lgkmcnt(6)
	v_mfma_f32_32x32x16_bf16 v[0:15], v[238:241], v[200:203], v[0:15]
	ds_read_b64_tr_b16 v[200:201], v195 offset:18688
	ds_read_b64_tr_b16 v[202:203], v195 offset:19200
	v_cvt_pk_bf16_f32 v250, v88, v89
	v_cvt_pk_bf16_f32 v251, v90, v91
	v_cvt_pk_bf16_f32 v252, v92, v93
	v_cvt_pk_bf16_f32 v253, v94, v95
	v_sub_f32_e32 v64, v64, v196
	v_sub_f32_e32 v65, v65, v196
	s_waitcnt lgkmcnt(6)
	v_mfma_f32_32x32x16_bf16 v[16:31], v[238:241], v[204:207], v[16:31]
	ds_read_b64_tr_b16 v[204:205], v195 offset:22848
	ds_read_b64_tr_b16 v[206:207], v195 offset:23360
	v_sub_f32_e32 v66, v66, v196
	v_sub_f32_e32 v67, v67, v196
	v_sub_f32_e32 v68, v68, v196
	v_sub_f32_e32 v69, v69, v196
	v_sub_f32_e32 v70, v70, v196
	v_sub_f32_e32 v71, v71, v196
	v_exp_f32_e32 v64, v64
	v_exp_f32_e32 v65, v65
	v_exp_f32_e32 v66, v66
	v_exp_f32_e32 v67, v67
	v_exp_f32_e32 v68, v68
	v_exp_f32_e32 v69, v69
	v_exp_f32_e32 v70, v70
	v_exp_f32_e32 v71, v71
	s_waitcnt lgkmcnt(6)
	v_mfma_f32_32x32x16_bf16 v[0:15], v[250:253], v[208:211], v[0:15]
	ds_read_b64_tr_b16 v[208:209], v195 offset:19712
	ds_read_b64_tr_b16 v[210:211], v195 offset:20224
	v_cvt_pk_bf16_f32 v242, v64, v65
	v_cvt_pk_bf16_f32 v243, v66, v67
	v_cvt_pk_bf16_f32 v244, v68, v69
	v_cvt_pk_bf16_f32 v245, v70, v71
	v_sub_f32_e32 v72, v72, v196
	v_sub_f32_e32 v73, v73, v196
	v_sub_f32_e32 v74, v74, v196
	s_waitcnt lgkmcnt(6)
	v_mfma_f32_32x32x16_bf16 v[16:31], v[250:253], v[212:215], v[16:31]
	ds_read_b64_tr_b16 v[212:213], v195 offset:23872
	ds_read_b64_tr_b16 v[214:215], v195 offset:24384
	v_sub_f32_e32 v75, v75, v196
	v_sub_f32_e32 v76, v76, v196
	v_sub_f32_e32 v77, v77, v196
	v_sub_f32_e32 v78, v78, v196
	v_sub_f32_e32 v79, v79, v196
	v_exp_f32_e32 v72, v72
	v_exp_f32_e32 v73, v73
	v_exp_f32_e32 v74, v74
	v_exp_f32_e32 v75, v75
	v_exp_f32_e32 v76, v76
	v_exp_f32_e32 v77, v77
	v_exp_f32_e32 v78, v78
	v_exp_f32_e32 v79, v79
	s_waitcnt lgkmcnt(6)
	v_mfma_f32_32x32x16_bf16 v[0:15], v[242:245], v[200:203], v[0:15]
	v_cvt_pk_bf16_f32 v250, v72, v73
	v_cvt_pk_bf16_f32 v251, v74, v75
	v_cvt_pk_bf16_f32 v252, v76, v77
	v_cvt_pk_bf16_f32 v253, v78, v79
	s_and_b64 vcc, exec, s[48:49]
	s_waitcnt lgkmcnt(4)
	v_mfma_f32_32x32x16_bf16 v[16:31], v[242:245], v[204:207], v[16:31]
	s_waitcnt lgkmcnt(2)
	v_mfma_f32_32x32x16_bf16 v[0:15], v[250:253], v[208:211], v[0:15]
	s_waitcnt lgkmcnt(0)
	v_mfma_f32_32x32x16_bf16 v[16:31], v[250:253], v[212:215], v[16:31]
	s_cbranch_vccnz .LBB0_355
	v_add_u32_e32 v236, s16, v138
	s_waitcnt vmcnt(0)
	ds_write_b128 v236, v[100:103] offset:16640

.LBB0_357:
	v_add_f32_e32 v80, 0, v80
	v_add_f32_e32 v80, v81, v80
	v_add_f32_e32 v80, v82, v80
	v_add_f32_e32 v80, v83, v80
	v_add_f32_e32 v80, v84, v80
	v_add_f32_e32 v80, v85, v80
	v_add_f32_e32 v80, v86, v80
	v_add_f32_e32 v80, v87, v80
	v_add_f32_e32 v80, v88, v80
	v_add_f32_e32 v80, v89, v80
	v_add_f32_e32 v80, v90, v80
	v_add_f32_e32 v80, v91, v80
	v_add_f32_e32 v80, v92, v80
	v_add_f32_e32 v80, v93, v80
	v_add_f32_e32 v80, v94, v80
	v_add_f32_e32 v80, v95, v80
	v_add_f32_e32 v64, v64, v80
	v_add_f32_e32 v64, v65, v64
	v_add_f32_e32 v64, v66, v64
	v_add_f32_e32 v64, v67, v64
	v_add_f32_e32 v64, v68, v64
	v_add_f32_e32 v64, v69, v64
	v_add_f32_e32 v64, v70, v64
	v_add_f32_e32 v64, v71, v64
	v_add_f32_e32 v64, v72, v64
	v_add_f32_e32 v64, v73, v64
	v_add_f32_e32 v64, v74, v64
	v_add_f32_e32 v64, v75, v64
	v_add_f32_e32 v64, v76, v64
	v_add_f32_e32 v64, v77, v64
	v_add_f32_e32 v64, v78, v64
	v_add_f32_e32 v191, v79, v64
	s_addk_i32 s90, 0xff80
	s_add_i32 s4, s56, 1
	v_fmac_f32_e32 v191, v198, v237
	s_cmp_lt_u32 s4, s55
	v_add_u32_e32 v192, 0xfffffe00, v192
	s_waitcnt lgkmcnt(0)
	s_barrier
	s_cbranch_scc0 .LBB0_360
	s_mov_b32 s57, s56
	s_branch .LBB0_337
